# E4 + O-rescale blocks: 32 v_pk_mul_f32 split into 64 v_mul_f32 (bit-identical), diff + windowed attention
# speedup vs baseline: 1.0248x; 1.0248x over previous
.LBB0_876:
	v_max_f32_e32 v96, v81, v81
	v_max_f32_e32 v99, v80, v80
	v_max_f32_e32 v96, v99, v96
	v_max_f32_e32 v99, v65, v65
	v_max_f32_e32 v100, v64, v64
	v_max_f32_e32 v99, v100, v99
	v_max3_f32 v96, v96, v82, v83
	v_max3_f32 v99, v99, v66, v67
	v_max3_f32 v96, v96, v84, v85
	v_max3_f32 v99, v99, v68, v69
	v_max3_f32 v96, v96, v86, v87
	v_max3_f32 v99, v99, v70, v71
	v_max3_f32 v96, v96, v88, v89
	v_max3_f32 v99, v99, v72, v73
	v_max3_f32 v96, v96, v90, v91
	v_max3_f32 v99, v99, v74, v75
	v_max3_f32 v96, v96, v92, v93
	v_max3_f32 v99, v99, v76, v77
	v_max3_f32 v96, v96, v94, v95
	v_max3_f32 v99, v99, v78, v79
	v_add_f32_e32 v96, v97, v96
	v_add_f32_e32 v99, v98, v99
	v_max_f32_e32 v96, v96, v99
	v_mov_b32_e32 v99, v96
	s_nop 1
	v_permlane32_swap_b32_e32 v96, v99
	v_max_f32_e32 v99, v99, v99
	v_max_f32_e32 v96, v96, v96
	v_max_f32_e32 v96, v96, v99
	v_sub_f32_e32 v99, v96, v112
	v_cmp_gt_f32_e32 vcc, s18, v99
	s_cmp_lg_u64 vcc, exec
	s_cselect_b64 s[78:79], -1, 0
	s_cmp_eq_u64 vcc, exec
	s_cbranch_scc1 .LBB0_880
	v_max_f32_e32 v96, v96, v96
	v_max_f32_e32 v99, v112, v112
	v_max_f32_e32 v203, v99, v96
	v_sub_f32_e32 v96, v112, v203
	v_exp_f32_e32 v96, v96
	s_nop 0
	v_cmp_neq_f32_e32 vcc, 1.0, v96
	s_cbranch_vccz .LBB0_879
	v_mul_f32_e32 v30, v96, v30
	v_mul_f32_e32 v31, v96, v31
	v_mul_f32_e32 v28, v96, v28
	v_mul_f32_e32 v29, v96, v29
	v_mul_f32_e32 v26, v96, v26
	v_mul_f32_e32 v27, v96, v27
	v_mul_f32_e32 v24, v96, v24
	v_mul_f32_e32 v25, v96, v25
	v_mul_f32_e32 v22, v96, v22
	v_mul_f32_e32 v23, v96, v23
	v_mul_f32_e32 v20, v96, v20
	v_mul_f32_e32 v21, v96, v21
	v_mul_f32_e32 v18, v96, v18
	v_mul_f32_e32 v19, v96, v19
	v_mul_f32_e32 v16, v96, v16
	v_mul_f32_e32 v17, v96, v17
	v_mul_f32_e32 v62, v96, v62
	v_mul_f32_e32 v63, v96, v63
	v_mul_f32_e32 v60, v96, v60
	v_mul_f32_e32 v61, v96, v61
	v_mul_f32_e32 v58, v96, v58
	v_mul_f32_e32 v59, v96, v59
	v_mul_f32_e32 v56, v96, v56
	v_mul_f32_e32 v57, v96, v57
	v_mul_f32_e32 v54, v96, v54
	v_mul_f32_e32 v55, v96, v55
	v_mul_f32_e32 v52, v96, v52
	v_mul_f32_e32 v53, v96, v53
	v_mul_f32_e32 v50, v96, v50
	v_mul_f32_e32 v51, v96, v51
	v_mul_f32_e32 v48, v96, v48
	v_mul_f32_e32 v49, v96, v49
	v_mul_f32_e32 v46, v96, v46
	v_mul_f32_e32 v47, v96, v47
	v_mul_f32_e32 v44, v96, v44
	v_mul_f32_e32 v45, v96, v45
	v_mul_f32_e32 v42, v96, v42
	v_mul_f32_e32 v43, v96, v43
	v_mul_f32_e32 v40, v96, v40
	v_mul_f32_e32 v41, v96, v41
	v_mul_f32_e32 v38, v96, v38
	v_mul_f32_e32 v39, v96, v39
	v_mul_f32_e32 v36, v96, v36
	v_mul_f32_e32 v37, v96, v37
	v_mul_f32_e32 v34, v96, v34
	v_mul_f32_e32 v35, v96, v35
	v_mul_f32_e32 v32, v96, v32
	v_mul_f32_e32 v33, v96, v33
	v_mul_f32_e32 v14, v96, v14
	v_mul_f32_e32 v15, v96, v15
	v_mul_f32_e32 v12, v96, v12
	v_mul_f32_e32 v13, v96, v13
	v_mul_f32_e32 v10, v96, v10
	v_mul_f32_e32 v11, v96, v11
	v_mul_f32_e32 v8, v96, v8
	v_mul_f32_e32 v9, v96, v9
	v_mul_f32_e32 v6, v96, v6
	v_mul_f32_e32 v7, v96, v7
	v_mul_f32_e32 v4, v96, v4
	v_mul_f32_e32 v5, v96, v5
	v_mul_f32_e32 v2, v96, v2
	v_mul_f32_e32 v3, v96, v3
	v_mul_f32_e32 v0, v96, v0
	v_mul_f32_e32 v1, v96, v1

.LBB0_897:
	v_max_f32_e32 v174, v113, v113
	v_max_f32_e32 v179, v112, v112
	v_max_f32_e32 v174, v179, v174
	v_max_f32_e32 v179, v97, v97
	v_max_f32_e32 v206, v96, v96
	v_max_f32_e32 v179, v206, v179
	v_max3_f32 v174, v174, v114, v115
	v_max3_f32 v179, v179, v98, v99
	v_max3_f32 v174, v174, v116, v117
	v_max3_f32 v179, v179, v100, v101
	v_max3_f32 v174, v174, v118, v119
	v_max3_f32 v179, v179, v102, v103
	v_max3_f32 v174, v174, v120, v121
	v_max3_f32 v179, v179, v104, v105
	v_max3_f32 v174, v174, v122, v123
	v_max3_f32 v179, v179, v106, v107
	v_max3_f32 v174, v174, v124, v125
	v_max3_f32 v179, v179, v108, v109
	v_max3_f32 v174, v174, v126, v127
	v_max3_f32 v179, v179, v110, v111
	v_add_f32_e32 v174, v204, v174
	v_add_f32_e32 v179, v205, v179
	v_max_f32_e32 v174, v174, v179
	v_mov_b32_e32 v179, v174
	s_nop 1
	v_permlane32_swap_b32_e32 v174, v179
	v_max_f32_e32 v179, v179, v179
	v_max_f32_e32 v174, v174, v174
	v_max_f32_e32 v174, v174, v179
	v_sub_f32_e32 v179, v174, v203
	v_cmp_gt_f32_e32 vcc, s18, v179
	s_cmp_lg_u64 vcc, exec
	s_cselect_b64 s[82:83], -1, 0
	s_cmp_eq_u64 vcc, exec
	s_cbranch_scc1 .LBB0_901
	v_max_f32_e32 v144, v174, v174
	v_max_f32_e32 v145, v203, v203
	v_max_f32_e32 v174, v145, v144
	v_sub_f32_e32 v144, v203, v174
	v_exp_f32_e32 v144, v144
	s_nop 0
	v_cmp_neq_f32_e32 vcc, 1.0, v144
	s_cbranch_vccz .LBB0_900
	v_mul_f32_e32 v30, v144, v30
	v_mul_f32_e32 v31, v144, v31
	v_mul_f32_e32 v28, v144, v28
	v_mul_f32_e32 v29, v144, v29
	v_mul_f32_e32 v26, v144, v26
	v_mul_f32_e32 v27, v144, v27
	v_mul_f32_e32 v24, v144, v24
	v_mul_f32_e32 v25, v144, v25
	v_mul_f32_e32 v22, v144, v22
	v_mul_f32_e32 v23, v144, v23
	v_mul_f32_e32 v20, v144, v20
	v_mul_f32_e32 v21, v144, v21
	v_mul_f32_e32 v18, v144, v18
	v_mul_f32_e32 v19, v144, v19
	v_mul_f32_e32 v16, v144, v16
	v_mul_f32_e32 v17, v144, v17
	v_mul_f32_e32 v62, v144, v62
	v_mul_f32_e32 v63, v144, v63
	v_mul_f32_e32 v60, v144, v60
	v_mul_f32_e32 v61, v144, v61
	v_mul_f32_e32 v58, v144, v58
	v_mul_f32_e32 v59, v144, v59
	v_mul_f32_e32 v56, v144, v56
	v_mul_f32_e32 v57, v144, v57
	v_mul_f32_e32 v54, v144, v54
	v_mul_f32_e32 v55, v144, v55
	v_mul_f32_e32 v52, v144, v52
	v_mul_f32_e32 v53, v144, v53
	v_mul_f32_e32 v50, v144, v50
	v_mul_f32_e32 v51, v144, v51
	v_mul_f32_e32 v48, v144, v48
	v_mul_f32_e32 v49, v144, v49
	v_mul_f32_e32 v46, v144, v46
	v_mul_f32_e32 v47, v144, v47
	v_mul_f32_e32 v44, v144, v44
	v_mul_f32_e32 v45, v144, v45
	v_mul_f32_e32 v42, v144, v42
	v_mul_f32_e32 v43, v144, v43
	v_mul_f32_e32 v40, v144, v40
	v_mul_f32_e32 v41, v144, v41
	v_mul_f32_e32 v38, v144, v38
	v_mul_f32_e32 v39, v144, v39
	v_mul_f32_e32 v36, v144, v36
	v_mul_f32_e32 v37, v144, v37
	v_mul_f32_e32 v34, v144, v34
	v_mul_f32_e32 v35, v144, v35
	v_mul_f32_e32 v32, v144, v32
	v_mul_f32_e32 v33, v144, v33
	v_mul_f32_e32 v14, v144, v14
	v_mul_f32_e32 v15, v144, v15
	v_mul_f32_e32 v12, v144, v12
	v_mul_f32_e32 v13, v144, v13
	v_mul_f32_e32 v10, v144, v10
	v_mul_f32_e32 v11, v144, v11
	v_mul_f32_e32 v8, v144, v8
	v_mul_f32_e32 v9, v144, v9
	v_mul_f32_e32 v6, v144, v6
	v_mul_f32_e32 v7, v144, v7
	v_mul_f32_e32 v4, v144, v4
	v_mul_f32_e32 v5, v144, v5
	v_mul_f32_e32 v2, v144, v2
	v_mul_f32_e32 v3, v144, v3
	v_mul_f32_e32 v0, v144, v0
	v_mul_f32_e32 v1, v144, v1

.LBB0_911:
	v_max_f32_e32 v96, v81, v81
	v_max_f32_e32 v99, v80, v80
	v_max_f32_e32 v96, v99, v96
	v_max_f32_e32 v99, v65, v65
	v_max_f32_e32 v100, v64, v64
	v_max_f32_e32 v99, v100, v99
	v_max3_f32 v96, v96, v82, v83
	v_max3_f32 v99, v99, v66, v67
	v_max3_f32 v96, v96, v84, v85
	v_max3_f32 v99, v99, v68, v69
	v_max3_f32 v96, v96, v86, v87
	v_max3_f32 v99, v99, v70, v71
	v_max3_f32 v96, v96, v88, v89
	v_max3_f32 v99, v99, v72, v73
	v_max3_f32 v96, v96, v90, v91
	v_max3_f32 v99, v99, v74, v75
	v_max3_f32 v96, v96, v92, v93
	v_max3_f32 v99, v99, v76, v77
	v_max3_f32 v96, v96, v94, v95
	v_max3_f32 v99, v99, v78, v79
	v_add_f32_e32 v96, v97, v96
	v_add_f32_e32 v99, v98, v99
	v_max_f32_e32 v96, v96, v99
	v_mov_b32_e32 v99, v96
	s_nop 1
	v_permlane32_swap_b32_e32 v96, v99
	v_max_f32_e32 v99, v99, v99
	v_max_f32_e32 v96, v96, v96
	v_max_f32_e32 v96, v96, v99
	v_sub_f32_e32 v99, v96, v174
	v_cmp_gt_f32_e32 vcc, s18, v99
	s_cmp_lg_u64 vcc, exec
	s_cselect_b64 s[78:79], -1, 0
	s_cmp_eq_u64 vcc, exec
	s_cbranch_scc1 .LBB0_915
	v_max_f32_e32 v96, v96, v96
	v_max_f32_e32 v99, v174, v174
	v_max_f32_e32 v203, v99, v96
	v_sub_f32_e32 v96, v174, v203
	v_exp_f32_e32 v96, v96
	s_nop 0
	v_cmp_neq_f32_e32 vcc, 1.0, v96
	s_cbranch_vccz .LBB0_914
	v_mul_f32_e32 v30, v96, v30
	v_mul_f32_e32 v31, v96, v31
	v_mul_f32_e32 v28, v96, v28
	v_mul_f32_e32 v29, v96, v29
	v_mul_f32_e32 v26, v96, v26
	v_mul_f32_e32 v27, v96, v27
	v_mul_f32_e32 v24, v96, v24
	v_mul_f32_e32 v25, v96, v25
	v_mul_f32_e32 v22, v96, v22
	v_mul_f32_e32 v23, v96, v23
	v_mul_f32_e32 v20, v96, v20
	v_mul_f32_e32 v21, v96, v21
	v_mul_f32_e32 v18, v96, v18
	v_mul_f32_e32 v19, v96, v19
	v_mul_f32_e32 v16, v96, v16
	v_mul_f32_e32 v17, v96, v17
	v_mul_f32_e32 v62, v96, v62
	v_mul_f32_e32 v63, v96, v63
	v_mul_f32_e32 v60, v96, v60
	v_mul_f32_e32 v61, v96, v61
	v_mul_f32_e32 v58, v96, v58
	v_mul_f32_e32 v59, v96, v59
	v_mul_f32_e32 v56, v96, v56
	v_mul_f32_e32 v57, v96, v57
	v_mul_f32_e32 v54, v96, v54
	v_mul_f32_e32 v55, v96, v55
	v_mul_f32_e32 v52, v96, v52
	v_mul_f32_e32 v53, v96, v53
	v_mul_f32_e32 v50, v96, v50
	v_mul_f32_e32 v51, v96, v51
	v_mul_f32_e32 v48, v96, v48
	v_mul_f32_e32 v49, v96, v49
	v_mul_f32_e32 v46, v96, v46
	v_mul_f32_e32 v47, v96, v47
	v_mul_f32_e32 v44, v96, v44
	v_mul_f32_e32 v45, v96, v45
	v_mul_f32_e32 v42, v96, v42
	v_mul_f32_e32 v43, v96, v43
	v_mul_f32_e32 v40, v96, v40
	v_mul_f32_e32 v41, v96, v41
	v_mul_f32_e32 v38, v96, v38
	v_mul_f32_e32 v39, v96, v39
	v_mul_f32_e32 v36, v96, v36
	v_mul_f32_e32 v37, v96, v37
	v_mul_f32_e32 v34, v96, v34
	v_mul_f32_e32 v35, v96, v35
	v_mul_f32_e32 v32, v96, v32
	v_mul_f32_e32 v33, v96, v33
	v_mul_f32_e32 v14, v96, v14
	v_mul_f32_e32 v15, v96, v15
	v_mul_f32_e32 v12, v96, v12
	v_mul_f32_e32 v13, v96, v13
	v_mul_f32_e32 v10, v96, v10
	v_mul_f32_e32 v11, v96, v11
	v_mul_f32_e32 v8, v96, v8
	v_mul_f32_e32 v9, v96, v9
	v_mul_f32_e32 v6, v96, v6
	v_mul_f32_e32 v7, v96, v7
	v_mul_f32_e32 v4, v96, v4
	v_mul_f32_e32 v5, v96, v5
	v_mul_f32_e32 v2, v96, v2
	v_mul_f32_e32 v3, v96, v3
	v_mul_f32_e32 v0, v96, v0
	v_mul_f32_e32 v1, v96, v1

.LBB0_930:
	v_max_f32_e32 v128, v113, v113
	v_max_f32_e32 v129, v112, v112
	v_max_f32_e32 v128, v129, v128
	v_max_f32_e32 v129, v97, v97
	v_max_f32_e32 v132, v96, v96
	v_max_f32_e32 v129, v132, v129
	v_max3_f32 v128, v128, v114, v115
	v_max3_f32 v129, v129, v98, v99
	v_max3_f32 v128, v128, v116, v117
	v_max3_f32 v129, v129, v100, v101
	v_max3_f32 v128, v128, v118, v119
	v_max3_f32 v129, v129, v102, v103
	v_max3_f32 v128, v128, v120, v121
	v_max3_f32 v129, v129, v104, v105
	v_max3_f32 v128, v128, v122, v123
	v_max3_f32 v129, v129, v106, v107
	v_max3_f32 v128, v128, v124, v125
	v_max3_f32 v129, v129, v108, v109
	v_max3_f32 v128, v128, v126, v127
	v_max3_f32 v129, v129, v110, v111
	v_add_f32_e32 v128, v130, v128
	v_add_f32_e32 v129, v131, v129
	v_max_f32_e32 v128, v128, v129
	v_mov_b32_e32 v129, v128
	s_nop 1
	v_permlane32_swap_b32_e32 v128, v129
	v_max_f32_e32 v129, v129, v129
	v_max_f32_e32 v128, v128, v128
	v_max_f32_e32 v128, v128, v129
	v_sub_f32_e32 v129, v128, v203
	v_cmp_gt_f32_e32 vcc, s18, v129
	s_cmp_lg_u64 vcc, exec
	s_cselect_b64 s[82:83], -1, 0
	s_cmp_eq_u64 vcc, exec
	s_cbranch_scc1 .LBB0_934
	v_max_f32_e32 v128, v128, v128
	v_max_f32_e32 v129, v203, v203
	v_max_f32_e32 v129, v129, v128
	v_sub_f32_e32 v128, v203, v129
	v_exp_f32_e32 v128, v128
	s_nop 0
	v_cmp_neq_f32_e32 vcc, 1.0, v128
	s_cbranch_vccz .LBB0_933
	v_mul_f32_e32 v30, v128, v30
	v_mul_f32_e32 v31, v128, v31
	v_mul_f32_e32 v28, v128, v28
	v_mul_f32_e32 v29, v128, v29
	v_mul_f32_e32 v26, v128, v26
	v_mul_f32_e32 v27, v128, v27
	v_mul_f32_e32 v24, v128, v24
	v_mul_f32_e32 v25, v128, v25
	v_mul_f32_e32 v22, v128, v22
	v_mul_f32_e32 v23, v128, v23
	v_mul_f32_e32 v20, v128, v20
	v_mul_f32_e32 v21, v128, v21
	v_mul_f32_e32 v18, v128, v18
	v_mul_f32_e32 v19, v128, v19
	v_mul_f32_e32 v16, v128, v16
	v_mul_f32_e32 v17, v128, v17
	v_mul_f32_e32 v62, v128, v62
	v_mul_f32_e32 v63, v128, v63
	v_mul_f32_e32 v60, v128, v60
	v_mul_f32_e32 v61, v128, v61
	v_mul_f32_e32 v58, v128, v58
	v_mul_f32_e32 v59, v128, v59
	v_mul_f32_e32 v56, v128, v56
	v_mul_f32_e32 v57, v128, v57
	v_mul_f32_e32 v54, v128, v54
	v_mul_f32_e32 v55, v128, v55
	v_mul_f32_e32 v52, v128, v52
	v_mul_f32_e32 v53, v128, v53
	v_mul_f32_e32 v50, v128, v50
	v_mul_f32_e32 v51, v128, v51
	v_mul_f32_e32 v48, v128, v48
	v_mul_f32_e32 v49, v128, v49
	v_mul_f32_e32 v46, v128, v46
	v_mul_f32_e32 v47, v128, v47
	v_mul_f32_e32 v44, v128, v44
	v_mul_f32_e32 v45, v128, v45
	v_mul_f32_e32 v42, v128, v42
	v_mul_f32_e32 v43, v128, v43
	v_mul_f32_e32 v40, v128, v40
	v_mul_f32_e32 v41, v128, v41
	v_mul_f32_e32 v38, v128, v38
	v_mul_f32_e32 v39, v128, v39
	v_mul_f32_e32 v36, v128, v36
	v_mul_f32_e32 v37, v128, v37
	v_mul_f32_e32 v34, v128, v34
	v_mul_f32_e32 v35, v128, v35
	v_mul_f32_e32 v32, v128, v32
	v_mul_f32_e32 v33, v128, v33
	v_mul_f32_e32 v14, v128, v14
	v_mul_f32_e32 v15, v128, v15
	v_mul_f32_e32 v12, v128, v12
	v_mul_f32_e32 v13, v128, v13
	v_mul_f32_e32 v10, v128, v10
	v_mul_f32_e32 v11, v128, v11
	v_mul_f32_e32 v8, v128, v8
	v_mul_f32_e32 v9, v128, v9
	v_mul_f32_e32 v6, v128, v6
	v_mul_f32_e32 v7, v128, v7
	v_mul_f32_e32 v4, v128, v4
	v_mul_f32_e32 v5, v128, v5
	v_mul_f32_e32 v2, v128, v2
	v_mul_f32_e32 v3, v128, v3
	v_mul_f32_e32 v0, v128, v0
	v_mul_f32_e32 v1, v128, v1

.LBB0_944:
	v_max_f32_e32 v96, v81, v81
	v_max_f32_e32 v99, v80, v80
	v_max_f32_e32 v96, v99, v96
	v_max_f32_e32 v99, v65, v65
	v_max_f32_e32 v100, v64, v64
	v_max_f32_e32 v99, v100, v99
	v_max3_f32 v96, v96, v82, v83
	v_max3_f32 v99, v99, v66, v67
	v_max3_f32 v96, v96, v84, v85
	v_max3_f32 v99, v99, v68, v69
	v_max3_f32 v96, v96, v86, v87
	v_max3_f32 v99, v99, v70, v71
	v_max3_f32 v96, v96, v88, v89
	v_max3_f32 v99, v99, v72, v73
	v_max3_f32 v96, v96, v90, v91
	v_max3_f32 v99, v99, v74, v75
	v_max3_f32 v96, v96, v92, v93
	v_max3_f32 v99, v99, v76, v77
	v_max3_f32 v96, v96, v94, v95
	v_max3_f32 v99, v99, v78, v79
	v_add_f32_e32 v96, v97, v96
	v_add_f32_e32 v99, v98, v99
	v_max_f32_e32 v96, v96, v99
	v_mov_b32_e32 v99, v96
	s_nop 1
	v_permlane32_swap_b32_e32 v96, v99
	v_max_f32_e32 v99, v99, v99
	v_max_f32_e32 v96, v96, v96
	v_max_f32_e32 v96, v96, v99
	v_sub_f32_e32 v99, v96, v129
	v_cmp_gt_f32_e32 vcc, s18, v99
	v_readlane_b32 s48, v255, 6
	s_cmp_lg_u64 vcc, exec
	v_readlane_b32 s49, v255, 7
	v_readlane_b32 s50, v255, 8
	v_readlane_b32 s51, v255, 9
	s_cselect_b64 s[76:77], -1, 0
	s_cmp_eq_u64 vcc, exec
	s_cbranch_scc1 .LBB0_948
	v_max_f32_e32 v96, v96, v96
	v_max_f32_e32 v99, v129, v129
	v_max_f32_e32 v99, v99, v96
	v_sub_f32_e32 v96, v129, v99
	v_exp_f32_e32 v96, v96
	s_nop 0
	v_cmp_neq_f32_e32 vcc, 1.0, v96
	s_cbranch_vccz .LBB0_947
	v_mul_f32_e32 v30, v96, v30
	v_mul_f32_e32 v31, v96, v31
	v_mul_f32_e32 v28, v96, v28
	v_mul_f32_e32 v29, v96, v29
	v_mul_f32_e32 v26, v96, v26
	v_mul_f32_e32 v27, v96, v27
	v_mul_f32_e32 v24, v96, v24
	v_mul_f32_e32 v25, v96, v25
	v_mul_f32_e32 v22, v96, v22
	v_mul_f32_e32 v23, v96, v23
	v_mul_f32_e32 v20, v96, v20
	v_mul_f32_e32 v21, v96, v21
	v_mul_f32_e32 v18, v96, v18
	v_mul_f32_e32 v19, v96, v19
	v_mul_f32_e32 v16, v96, v16
	v_mul_f32_e32 v17, v96, v17
	v_mul_f32_e32 v62, v96, v62
	v_mul_f32_e32 v63, v96, v63
	v_mul_f32_e32 v60, v96, v60
	v_mul_f32_e32 v61, v96, v61
	v_mul_f32_e32 v58, v96, v58
	v_mul_f32_e32 v59, v96, v59
	v_mul_f32_e32 v56, v96, v56
	v_mul_f32_e32 v57, v96, v57
	v_mul_f32_e32 v54, v96, v54
	v_mul_f32_e32 v55, v96, v55
	v_mul_f32_e32 v52, v96, v52
	v_mul_f32_e32 v53, v96, v53
	v_mul_f32_e32 v50, v96, v50
	v_mul_f32_e32 v51, v96, v51
	v_mul_f32_e32 v48, v96, v48
	v_mul_f32_e32 v49, v96, v49
	v_mul_f32_e32 v46, v96, v46
	v_mul_f32_e32 v47, v96, v47
	v_mul_f32_e32 v44, v96, v44
	v_mul_f32_e32 v45, v96, v45
	v_mul_f32_e32 v42, v96, v42
	v_mul_f32_e32 v43, v96, v43
	v_mul_f32_e32 v40, v96, v40
	v_mul_f32_e32 v41, v96, v41
	v_mul_f32_e32 v38, v96, v38
	v_mul_f32_e32 v39, v96, v39
	v_mul_f32_e32 v36, v96, v36
	v_mul_f32_e32 v37, v96, v37
	v_mul_f32_e32 v34, v96, v34
	v_mul_f32_e32 v35, v96, v35
	v_mul_f32_e32 v32, v96, v32
	v_mul_f32_e32 v33, v96, v33
	v_mul_f32_e32 v14, v96, v14
	v_mul_f32_e32 v15, v96, v15
	v_mul_f32_e32 v12, v96, v12
	v_mul_f32_e32 v13, v96, v13
	v_mul_f32_e32 v10, v96, v10
	v_mul_f32_e32 v11, v96, v11
	v_mul_f32_e32 v8, v96, v8
	v_mul_f32_e32 v9, v96, v9
	v_mul_f32_e32 v6, v96, v6
	v_mul_f32_e32 v7, v96, v7
	v_mul_f32_e32 v4, v96, v4
	v_mul_f32_e32 v5, v96, v5
	v_mul_f32_e32 v2, v96, v2
	v_mul_f32_e32 v3, v96, v3
	v_mul_f32_e32 v0, v96, v0
	v_mul_f32_e32 v1, v96, v1

.LBB0_988:
	v_max_f32_e32 v0, v67, v67
	v_max_f32_e32 v136, v66, v66
	v_max_f32_e32 v0, v136, v0
	v_max_f32_e32 v136, v35, v35
	v_max_f32_e32 v137, v34, v34
	v_max_f32_e32 v136, v137, v136
	v_max3_f32 v0, v0, v68, v69
	v_max3_f32 v136, v136, v36, v37
	v_max3_f32 v0, v0, v70, v71
	v_max3_f32 v136, v136, v38, v39
	v_max3_f32 v0, v0, v72, v73
	v_max3_f32 v136, v136, v40, v41
	v_max3_f32 v0, v0, v74, v75
	v_max3_f32 v136, v136, v42, v43
	v_max3_f32 v0, v0, v76, v77
	v_max3_f32 v136, v136, v44, v45
	v_max3_f32 v0, v0, v78, v79
	v_max3_f32 v136, v136, v46, v47
	v_max3_f32 v0, v0, v80, v81
	v_max3_f32 v136, v136, v48, v49
	v_add_f32_e32 v0, v134, v0
	v_add_f32_e32 v136, v135, v136
	v_max_f32_e32 v0, v0, v136
	v_mov_b32_e32 v136, v0
	s_nop 1
	v_permlane32_swap_b32_e32 v0, v136
	v_max_f32_e32 v136, v136, v136
	v_max_f32_e32 v0, v0, v0
	v_max_f32_e32 v0, v0, v136
	v_sub_f32_e32 v136, v0, v162
	v_cmp_gt_f32_e32 vcc, s4, v136
	s_cmp_lg_u64 vcc, exec
	s_cselect_b64 s[10:11], -1, 0
	s_cmp_eq_u64 vcc, exec
	s_cbranch_scc1 .LBB0_993
	v_max_f32_e32 v0, v0, v0
	v_max_f32_e32 v114, v162, v162
	v_max_f32_e32 v163, v114, v0
	v_sub_f32_e32 v0, v162, v163
	v_exp_f32_e32 v0, v0
	s_nop 0
	v_cmp_neq_f32_e32 vcc, 1.0, v0
	s_cbranch_vccz .LBB0_991
	v_mul_f32_e32 v32, v0, v32
	v_mul_f32_e32 v33, v0, v33
	v_mul_f32_e32 v30, v0, v30
	v_mul_f32_e32 v31, v0, v31
	v_mul_f32_e32 v28, v0, v28
	v_mul_f32_e32 v29, v0, v29
	v_mul_f32_e32 v26, v0, v26
	v_mul_f32_e32 v27, v0, v27
	v_mul_f32_e32 v24, v0, v24
	v_mul_f32_e32 v25, v0, v25
	v_mul_f32_e32 v22, v0, v22
	v_mul_f32_e32 v23, v0, v23
	v_mul_f32_e32 v20, v0, v20
	v_mul_f32_e32 v21, v0, v21
	v_mul_f32_e32 v18, v0, v18
	v_mul_f32_e32 v19, v0, v19
	v_mul_f32_e32 v16, v0, v16
	v_mul_f32_e32 v17, v0, v17
	v_mul_f32_e32 v14, v0, v14
	v_mul_f32_e32 v15, v0, v15
	v_mul_f32_e32 v12, v0, v12
	v_mul_f32_e32 v13, v0, v13
	v_mul_f32_e32 v10, v0, v10
	v_mul_f32_e32 v11, v0, v11
	v_mul_f32_e32 v8, v0, v8
	v_mul_f32_e32 v9, v0, v9
	v_mul_f32_e32 v6, v0, v6
	v_mul_f32_e32 v7, v0, v7
	v_mul_f32_e32 v4, v0, v4
	v_mul_f32_e32 v5, v0, v5
	v_mul_f32_e32 v2, v0, v2
	v_mul_f32_e32 v3, v0, v3

.LBB0_1004:
	v_max_f32_e32 v0, v83, v83
	v_max_f32_e32 v136, v82, v82
	v_max_f32_e32 v0, v136, v0
	v_max_f32_e32 v136, v51, v51
	v_max_f32_e32 v137, v50, v50
	v_max_f32_e32 v136, v137, v136
	v_max3_f32 v0, v0, v84, v85
	v_max3_f32 v136, v136, v52, v53
	v_max3_f32 v0, v0, v86, v87
	v_max3_f32 v136, v136, v54, v55
	v_max3_f32 v0, v0, v88, v89
	v_max3_f32 v136, v136, v56, v57
	v_max3_f32 v0, v0, v90, v91
	v_max3_f32 v136, v136, v58, v59
	v_max3_f32 v0, v0, v92, v93
	v_max3_f32 v136, v136, v60, v61
	v_max3_f32 v0, v0, v94, v95
	v_max3_f32 v136, v136, v62, v63
	v_max3_f32 v0, v0, v96, v97
	v_max3_f32 v136, v136, v64, v65
	v_add_f32_e32 v0, v134, v0
	v_add_f32_e32 v136, v135, v136
	v_max_f32_e32 v0, v0, v136
	v_mov_b32_e32 v136, v0
	s_nop 1
	v_permlane32_swap_b32_e32 v0, v136
	v_max_f32_e32 v136, v136, v136
	v_max_f32_e32 v0, v0, v0
	v_max_f32_e32 v0, v0, v136
	v_sub_f32_e32 v136, v0, v163
	v_cmp_gt_f32_e32 vcc, s4, v136
	s_cmp_lg_u64 vcc, exec
	s_cselect_b64 s[8:9], -1, 0
	s_cmp_eq_u64 vcc, exec
	s_cbranch_scc1 .LBB0_1009
	v_max_f32_e32 v0, v0, v0
	v_max_f32_e32 v114, v163, v163
	v_max_f32_e32 v162, v114, v0
	v_sub_f32_e32 v0, v163, v162
	v_exp_f32_e32 v0, v0
	s_nop 0
	v_cmp_neq_f32_e32 vcc, 1.0, v0
	s_cbranch_vccz .LBB0_1007
	v_mul_f32_e32 v32, v0, v32
	v_mul_f32_e32 v33, v0, v33
	v_mul_f32_e32 v30, v0, v30
	v_mul_f32_e32 v31, v0, v31
	v_mul_f32_e32 v28, v0, v28
	v_mul_f32_e32 v29, v0, v29
	v_mul_f32_e32 v26, v0, v26
	v_mul_f32_e32 v27, v0, v27
	v_mul_f32_e32 v24, v0, v24
	v_mul_f32_e32 v25, v0, v25
	v_mul_f32_e32 v22, v0, v22
	v_mul_f32_e32 v23, v0, v23
	v_mul_f32_e32 v20, v0, v20
	v_mul_f32_e32 v21, v0, v21
	v_mul_f32_e32 v18, v0, v18
	v_mul_f32_e32 v19, v0, v19
	v_mul_f32_e32 v16, v0, v16
	v_mul_f32_e32 v17, v0, v17
	v_mul_f32_e32 v14, v0, v14
	v_mul_f32_e32 v15, v0, v15
	v_mul_f32_e32 v12, v0, v12
	v_mul_f32_e32 v13, v0, v13
	v_mul_f32_e32 v10, v0, v10
	v_mul_f32_e32 v11, v0, v11
	v_mul_f32_e32 v8, v0, v8
	v_mul_f32_e32 v9, v0, v9
	v_mul_f32_e32 v6, v0, v6
	v_mul_f32_e32 v7, v0, v7
	v_mul_f32_e32 v4, v0, v4
	v_mul_f32_e32 v5, v0, v5
	v_mul_f32_e32 v2, v0, v2
	v_mul_f32_e32 v3, v0, v3
